# attention phase: static s_setprio 1 for waves 4-7
# speedup vs baseline: 1.0059x; 1.0059x over previous
.LBB0_355:
	v_readfirstlane_b32 s2, v190
	s_lshr_b32 s2, s2, 8
	s_cmp_lg_u32 s2, 0
	s_cbranch_scc0 .Lattn_prio_done
	s_setprio 1

.LBB0_732:
	s_setprio 0
	v_readlane_b32 s54, v236, 39
	s_add_i32 s54, s54, 1
	v_readlane_b32 s53, v236, 33
	s_cmp_lt_i32 s54, s53
	s_cbranch_scc0 .LBB0_183
	v_readlane_b32 s0, v237, 8
	v_readlane_b32 s1, v237, 9
	v_readlane_b32 s56, v236, 36
	s_andn2_b64 vcc, exec, s[0:1]
	s_mov_b64 s[0:1], -1
	v_readlane_b32 s57, v236, 37
	v_readlane_b32 s55, v236, 41
	s_cbranch_vccnz .LBB0_779
	s_waitcnt vmcnt(0)
	s_waitcnt vmcnt(0) lgkmcnt(0)
	s_barrier
	s_and_saveexec_b64 s[0:1], s[90:91]
	s_cbranch_execz .LBB0_778
	v_readlane_b32 s2, v237, 2
	v_readlane_b32 s4, v236, 20
	v_readlane_b32 s3, v237, 3
	s_waitcnt vmcnt(0) expcnt(0) lgkmcnt(0)
	v_mov_b32_e32 v0, s4
	ds_read_b32 v2, v0
	v_readlane_b32 s4, v236, 21
	s_waitcnt lgkmcnt(0)
	v_cmp_ne_u32_e32 vcc, 0, v2
	v_mov_b32_e32 v0, s4
	ds_read_b32 v0, v0
	s_cbranch_vccnz .LBB0_749
	s_add_u32 s4, s2, 0x1000
	s_addc_u32 s5, s3, 0
	s_add_u32 s6, s2, 0x1100
	s_addc_u32 s7, s3, 0
	s_add_u32 s22, s2, 0x1200
	s_addc_u32 s23, s3, 0
	s_add_u32 s28, s2, 0x1300
	s_addc_u32 s29, s3, 0
	s_mov_b32 s27, 1
	s_mov_b64 s[30:31], 0
	s_branch .LBB0_739
